# SSM pass 2: recurrence as in-place scalar v_fmac on the MFMA outputs, bf16 image writes read the accumulators directly
# speedup vs baseline: 1.0051x; 1.0007x over previous
.LBB0_509:
	v_mfma_f32_32x32x16_bf16 v[50:65], v[138:141], v[78:81], 0
	s_add_i32 s76, s76, 1
	v_lshl_add_u64 v[158:159], v[158:159], 0, s[70:71]
	s_cmp_eq_u32 s76, 16
	v_mfma_f32_32x32x16_bf16 v[2:17], v[138:141], v[66:69], 0
	v_mfma_f32_32x32x16_bf16 v[18:33], v[138:141], v[70:73], 0
	v_mfma_f32_32x32x16_bf16 v[34:49], v[138:141], v[74:77], 0
	v_xor_b32_e32 v254, 0x80000000, v156
	v_xor_b32_e32 v255, 0x80000000, v157
	s_nop 9
	v_fmac_f32_e32 v50, v160, v162
	v_fmac_f32_e32 v2, v161, v163
	v_fmac_f32_e32 v18, v160, v164
	v_fmac_f32_e32 v34, v161, v165
	v_fmac_f32_e32 v50, v254, v164
	v_fmac_f32_e32 v2, v255, v165
	v_fmac_f32_e32 v18, v156, v162
	v_fmac_f32_e32 v34, v157, v163
	v_fmac_f32_e32 v51, v160, v50
	v_fmac_f32_e32 v3, v161, v2
	v_fmac_f32_e32 v19, v160, v18
	v_fmac_f32_e32 v35, v161, v34
	v_fmac_f32_e32 v51, v254, v18
	v_fmac_f32_e32 v3, v255, v34
	v_fmac_f32_e32 v19, v156, v50
	v_fmac_f32_e32 v35, v157, v2
	v_fmac_f32_e32 v52, v160, v51
	v_fmac_f32_e32 v4, v161, v3
	v_fmac_f32_e32 v20, v160, v19
	v_fmac_f32_e32 v36, v161, v35
	v_fmac_f32_e32 v52, v254, v19
	v_fmac_f32_e32 v4, v255, v35
	v_fmac_f32_e32 v20, v156, v51
	v_fmac_f32_e32 v36, v157, v3
	v_fmac_f32_e32 v53, v160, v52
	v_fmac_f32_e32 v5, v161, v4
	v_fmac_f32_e32 v21, v160, v20
	v_fmac_f32_e32 v37, v161, v36
	v_fmac_f32_e32 v53, v254, v20
	v_fmac_f32_e32 v5, v255, v36
	v_fmac_f32_e32 v21, v156, v52
	v_fmac_f32_e32 v37, v157, v4
	v_fmac_f32_e32 v54, v160, v53
	v_fmac_f32_e32 v6, v161, v5
	v_fmac_f32_e32 v22, v160, v21
	v_fmac_f32_e32 v38, v161, v37
	v_fmac_f32_e32 v54, v254, v21
	v_fmac_f32_e32 v6, v255, v37
	v_fmac_f32_e32 v22, v156, v53
	v_fmac_f32_e32 v38, v157, v5
	v_fmac_f32_e32 v55, v160, v54
	v_fmac_f32_e32 v7, v161, v6
	v_fmac_f32_e32 v23, v160, v22
	v_fmac_f32_e32 v39, v161, v38
	v_fmac_f32_e32 v55, v254, v22
	v_fmac_f32_e32 v7, v255, v38
	v_fmac_f32_e32 v23, v156, v54
	v_fmac_f32_e32 v39, v157, v6
	v_fmac_f32_e32 v56, v160, v55
	v_fmac_f32_e32 v8, v161, v7
	v_fmac_f32_e32 v24, v160, v23
	v_fmac_f32_e32 v40, v161, v39
	v_fmac_f32_e32 v56, v254, v23
	v_fmac_f32_e32 v8, v255, v39
	v_fmac_f32_e32 v24, v156, v55
	v_fmac_f32_e32 v40, v157, v7
	v_fmac_f32_e32 v57, v160, v56
	v_fmac_f32_e32 v9, v161, v8
	v_fmac_f32_e32 v25, v160, v24
	v_fmac_f32_e32 v41, v161, v40
	v_fmac_f32_e32 v57, v254, v24
	v_fmac_f32_e32 v9, v255, v40
	v_fmac_f32_e32 v25, v156, v56
	v_fmac_f32_e32 v41, v157, v8
	v_fmac_f32_e32 v58, v160, v57
	v_fmac_f32_e32 v10, v161, v9
	v_fmac_f32_e32 v26, v160, v25
	v_fmac_f32_e32 v42, v161, v41
	v_fmac_f32_e32 v58, v254, v25
	v_fmac_f32_e32 v10, v255, v41
	v_fmac_f32_e32 v26, v156, v57
	v_fmac_f32_e32 v42, v157, v9
	v_fmac_f32_e32 v59, v160, v58
	v_fmac_f32_e32 v11, v161, v10
	v_fmac_f32_e32 v27, v160, v26
	v_fmac_f32_e32 v43, v161, v42
	v_fmac_f32_e32 v59, v254, v26
	v_fmac_f32_e32 v11, v255, v42
	v_fmac_f32_e32 v27, v156, v58
	v_fmac_f32_e32 v43, v157, v10
	v_fmac_f32_e32 v60, v160, v59
	v_fmac_f32_e32 v12, v161, v11
	v_fmac_f32_e32 v28, v160, v27
	v_fmac_f32_e32 v44, v161, v43
	v_fmac_f32_e32 v60, v254, v27
	v_fmac_f32_e32 v12, v255, v43
	v_fmac_f32_e32 v28, v156, v59
	v_fmac_f32_e32 v44, v157, v11
	v_fmac_f32_e32 v61, v160, v60
	v_fmac_f32_e32 v13, v161, v12
	v_fmac_f32_e32 v29, v160, v28
	v_fmac_f32_e32 v45, v161, v44
	v_fmac_f32_e32 v61, v254, v28
	v_fmac_f32_e32 v13, v255, v44
	v_fmac_f32_e32 v29, v156, v60
	v_fmac_f32_e32 v45, v157, v12
	v_fmac_f32_e32 v62, v160, v61
	v_fmac_f32_e32 v14, v161, v13
	v_fmac_f32_e32 v30, v160, v29
	v_fmac_f32_e32 v46, v161, v45
	v_fmac_f32_e32 v62, v254, v29
	v_fmac_f32_e32 v14, v255, v45
	v_fmac_f32_e32 v30, v156, v61
	v_fmac_f32_e32 v46, v157, v13
	v_fmac_f32_e32 v63, v160, v62
	v_fmac_f32_e32 v15, v161, v14
	v_fmac_f32_e32 v31, v160, v30
	v_fmac_f32_e32 v47, v161, v46
	v_fmac_f32_e32 v63, v254, v30
	v_fmac_f32_e32 v15, v255, v46
	v_fmac_f32_e32 v31, v156, v62
	v_fmac_f32_e32 v47, v157, v14
	v_fmac_f32_e32 v64, v160, v63
	v_fmac_f32_e32 v16, v161, v15
	v_fmac_f32_e32 v32, v160, v31
	v_fmac_f32_e32 v48, v161, v47
	v_fmac_f32_e32 v64, v254, v31
	v_fmac_f32_e32 v16, v255, v47
	v_fmac_f32_e32 v32, v156, v63
	v_fmac_f32_e32 v48, v157, v15
	v_fmac_f32_e32 v65, v160, v64
	v_fmac_f32_e32 v17, v161, v16
	v_fmac_f32_e32 v33, v160, v32
	v_fmac_f32_e32 v49, v161, v48
	v_fmac_f32_e32 v65, v254, v32
	v_fmac_f32_e32 v17, v255, v48
	v_fmac_f32_e32 v33, v156, v64
	v_fmac_f32_e32 v49, v157, v16
	v_mov_b32_e32 v162, v65
	v_mov_b32_e32 v163, v17
	v_mov_b32_e32 v164, v33
	v_mov_b32_e32 v165, v49
	v_cvt_pk_bf16_f32 v250, v2, v3
	v_cvt_pk_bf16_f32 v251, v4, v5
	ds_write_b64 v185, v[250:251] offset:2304
	v_cvt_pk_bf16_f32 v252, v6, v7
	v_cvt_pk_bf16_f32 v253, v8, v9
	ds_write_b64 v185, v[252:253] offset:2320
	v_cvt_pk_bf16_f32 v250, v10, v11
	v_cvt_pk_bf16_f32 v251, v12, v13
	ds_write_b64 v185, v[250:251] offset:2336
	v_cvt_pk_bf16_f32 v252, v14, v15
	v_cvt_pk_bf16_f32 v253, v16, v17
	ds_write_b64 v185, v[252:253] offset:2352
	v_mfma_f32_32x32x16_bf16 v[2:17], v[94:97], v[138:141], 0
	v_cvt_pk_bf16_f32 v250, v50, v51
	v_cvt_pk_bf16_f32 v251, v52, v53
	ds_write_b64 v185, v[250:251]
	v_cvt_pk_bf16_f32 v252, v54, v55
	v_cvt_pk_bf16_f32 v253, v56, v57
	ds_write_b64 v185, v[252:253] offset:16
	v_cvt_pk_bf16_f32 v250, v58, v59
	v_cvt_pk_bf16_f32 v251, v60, v61
	ds_write_b64 v185, v[250:251] offset:32
	v_cvt_pk_bf16_f32 v252, v62, v63
	v_cvt_pk_bf16_f32 v253, v64, v65
	ds_write_b64 v185, v[252:253] offset:48
	v_mfma_f32_32x32x16_bf16 v[2:17], v[98:101], v[138:141], v[2:17]
	v_cvt_pk_bf16_f32 v250, v18, v19
	v_cvt_pk_bf16_f32 v251, v20, v21
	ds_write_b64 v185, v[250:251] offset:4608
	v_cvt_pk_bf16_f32 v252, v22, v23
	v_cvt_pk_bf16_f32 v253, v24, v25
	ds_write_b64 v185, v[252:253] offset:4624
	v_cvt_pk_bf16_f32 v250, v26, v27
	v_cvt_pk_bf16_f32 v251, v28, v29
	ds_write_b64 v185, v[250:251] offset:4640
	v_cvt_pk_bf16_f32 v252, v30, v31
	v_cvt_pk_bf16_f32 v253, v32, v33
	ds_write_b64 v185, v[252:253] offset:4656
	v_cvt_pk_bf16_f32 v250, v34, v35
	v_cvt_pk_bf16_f32 v251, v36, v37
	ds_write_b64 v185, v[250:251] offset:6912
	v_cvt_pk_bf16_f32 v252, v38, v39
	v_cvt_pk_bf16_f32 v253, v40, v41
	ds_write_b64 v185, v[252:253] offset:6928
	v_cvt_pk_bf16_f32 v250, v42, v43
	v_cvt_pk_bf16_f32 v251, v44, v45
	ds_write_b64 v185, v[250:251] offset:6944
	v_cvt_pk_bf16_f32 v252, v46, v47
	v_cvt_pk_bf16_f32 v253, v48, v49
	ds_write_b64 v185, v[252:253] offset:6960
	s_waitcnt lgkmcnt(0)
	ds_read_b64_tr_b16 v[18:19], v186
	ds_read_b64_tr_b16 v[20:21], v186 offset:288
	ds_read_b64_tr_b16 v[22:23], v186 offset:1152
	ds_read_b64_tr_b16 v[24:25], v186 offset:1440
	v_mov_b64_e32 v[140:141], v[136:137]
	v_mov_b64_e32 v[138:139], v[134:135]
	s_waitcnt lgkmcnt(2)
	v_mfma_f32_32x32x16_bf16 v[2:17], v[102:105], v[18:21], v[2:17]
	s_waitcnt lgkmcnt(0)
	v_mfma_f32_32x32x16_bf16 v[2:17], v[106:109], v[22:25], v[2:17]
	ds_read_b64_tr_b16 v[18:19], v186 offset:2304
	ds_read_b64_tr_b16 v[20:21], v186 offset:2592
	ds_read_b64_tr_b16 v[22:23], v186 offset:3456
	ds_read_b64_tr_b16 v[24:25], v186 offset:3744
	s_waitcnt lgkmcnt(2)
	v_mfma_f32_32x32x16_bf16 v[2:17], v[110:113], v[18:21], v[2:17]
	s_waitcnt lgkmcnt(0)
	v_mfma_f32_32x32x16_bf16 v[2:17], v[114:117], v[22:25], v[2:17]
	ds_read_b64_tr_b16 v[18:19], v186 offset:4608
	ds_read_b64_tr_b16 v[20:21], v186 offset:4896
	ds_read_b64_tr_b16 v[22:23], v186 offset:5760
	ds_read_b64_tr_b16 v[24:25], v186 offset:6048
	s_waitcnt lgkmcnt(2)
	v_mfma_f32_32x32x16_bf16 v[2:17], v[118:121], v[18:21], v[2:17]
	s_waitcnt lgkmcnt(0)
	v_mfma_f32_32x32x16_bf16 v[2:17], v[122:125], v[22:25], v[2:17]
	ds_read_b64_tr_b16 v[18:19], v186 offset:6912
	ds_read_b64_tr_b16 v[20:21], v186 offset:7200
	ds_read_b64_tr_b16 v[22:23], v186 offset:8064
	ds_read_b64_tr_b16 v[24:25], v186 offset:8352
	s_waitcnt lgkmcnt(0)
	s_waitcnt lgkmcnt(2)
	v_mfma_f32_32x32x16_bf16 v[2:17], v[126:129], v[18:21], v[2:17]
	s_waitcnt lgkmcnt(0)
	v_mfma_f32_32x32x16_bf16 v[2:17], v[130:133], v[22:25], v[2:17]
	s_nop 11
	v_mul_f32_e32 v11, 0x3d372713, v3
	v_mul_f32_e32 v12, 0x3d372713, v4
	v_mul_f32_e32 v11, v3, v11
	v_mul_f32_e32 v12, v4, v12
	v_fma_f32 v11, v3, v11, v3
	v_fma_f32 v12, v4, v12, v4
	v_mul_f32_e32 v11, 0x3fcc422a, v11
	v_mul_f32_e32 v12, 0x3fcc422a, v12
	v_mul_f32_e32 v10, 0x3d372713, v2
	v_mul_f32_e32 v11, 0xbfb8aa3b, v11
	v_mul_f32_e32 v12, 0xbfb8aa3b, v12
	v_mul_f32_e32 v10, v2, v10
	v_exp_f32_e32 v11, v11
	v_exp_f32_e32 v12, v12
	v_fma_f32 v10, v2, v10, v2
	v_mul_f32_e32 v10, 0x3fcc422a, v10
	v_mul_f32_e32 v10, 0xbfb8aa3b, v10
	v_exp_f32_e32 v10, v10
	v_add_f32_e32 v11, 1.0, v11
	v_add_f32_e32 v12, 1.0, v12
	v_mul_f32_e32 v13, 0x3d372713, v5
	v_rcp_f32_e32 v11, v11
	v_rcp_f32_e32 v12, v12
	v_mul_f32_e32 v13, v5, v13
	v_fma_f32 v13, v5, v13, v5
	v_mul_f32_e32 v13, 0x3fcc422a, v13
	v_add_f32_e32 v10, 1.0, v10
	v_mul_f32_e32 v13, 0xbfb8aa3b, v13
	v_rcp_f32_e32 v10, v10
	v_exp_f32_e32 v13, v13
	v_mul_f32_e32 v3, v3, v11
	v_mul_f32_e32 v4, v4, v12
	v_mul_f32_e32 v11, 0x3d372713, v6
	v_mul_f32_e32 v12, 0x3d372713, v7
	v_mul_f32_e32 v11, v6, v11
	v_mul_f32_e32 v12, v7, v12
	v_fma_f32 v11, v6, v11, v6
	v_fma_f32 v12, v7, v12, v7
	v_mul_f32_e32 v11, 0x3fcc422a, v11
	v_mul_f32_e32 v12, 0x3fcc422a, v12
	v_mul_f32_e32 v2, v2, v10
	v_add_f32_e32 v10, 1.0, v13
	v_mul_f32_e32 v11, 0xbfb8aa3b, v11
	v_mul_f32_e32 v12, 0xbfb8aa3b, v12
	v_rcp_f32_e32 v10, v10
	v_exp_f32_e32 v11, v11
	v_exp_f32_e32 v12, v12
	v_mul_f32_e32 v13, 0x3d372713, v9
	v_mul_f32_e32 v5, v5, v10
	v_add_f32_e32 v10, 1.0, v11
	v_add_f32_e32 v11, 1.0, v12
	v_mul_f32_e32 v12, 0x3d372713, v8
	v_mul_f32_e32 v12, v8, v12
	v_mul_f32_e32 v13, v9, v13
	v_fma_f32 v12, v8, v12, v8
	v_fma_f32 v13, v9, v13, v9
	v_mul_f32_e32 v12, 0x3fcc422a, v12
	v_mul_f32_e32 v13, 0x3fcc422a, v13
	v_mul_f32_e32 v12, 0xbfb8aa3b, v12
	v_mul_f32_e32 v13, 0xbfb8aa3b, v13
	v_exp_f32_e32 v12, v12
	v_exp_f32_e32 v13, v13
	v_rcp_f32_e32 v10, v10
	v_rcp_f32_e32 v11, v11
	v_add_f32_e32 v12, 1.0, v12
	v_add_f32_e32 v13, 1.0, v13
	v_rcp_f32_e32 v12, v12
	v_rcp_f32_e32 v13, v13
	v_cvt_pk_bf16_f32 v2, v2, v3
	v_cvt_pk_bf16_f32 v3, v4, v5
	v_mul_f32_e32 v6, v6, v10
	v_mul_f32_e32 v7, v7, v11
	v_mul_f32_e32 v8, v8, v12
	v_mul_f32_e32 v9, v9, v13
	v_cvt_pk_bf16_f32 v4, v6, v7
	v_cvt_pk_bf16_f32 v5, v8, v9
	global_store_dwordx2 v[168:169], v[2:3], off
	global_store_dwordx2 v[168:169], v[4:5], off offset:16
	v_lshl_add_u64 v[168:169], v[168:169], 0, s[70:71]
	s_cbranch_scc1 .LBB0_493
	s_waitcnt vmcnt(2)
	v_mov_b64_e32 v[136:137], v[84:85]
	v_mov_b64_e32 v[134:135], v[82:83]
	v_mov_b64_e32 v[82:83], v[90:91]
	v_mov_b64_e32 v[84:85], v[92:93]
	v_mov_b64_e32 v[92:93], v[88:89]
	s_cmp_gt_u32 s76, 11
	v_mov_b64_e32 v[90:91], v[86:87]
	s_cbranch_scc1 .LBB0_509
	s_branch .Lssm2_load
